# static scan placement: both workgroups of a CU (b, b+256) run scan items; queue hands out items 192.. (guarded on gridDim==512)
# speedup vs baseline: 1.0164x; 1.0110x over previous
; __device__ __forceinline__ unsigned char* WS(const Params& p) { unsigned z = 0; asm volatile("" : "+s"(z)); return p.ws + z; }
; __device__ __forceinline__ int opaque_tid() { int t = threadIdx.x; asm volatile("" : "+v"(t)); return t; }
; __device__ __forceinline__ void run_phase(const Params& p, int ph, char* lds, int mode) {
;     ...
;       unsigned* ctr = (unsigned*)(WS(p) + OFF_CTRL) + (mode ? 8 + mode : l);
;       int* sh = (int*)(lds + 74240);
;       for (;;) {
;         __syncthreads();
;         if (opaque_tid() == 0) *sh = (int)atomicAdd(ctr, 1u);
;         __syncthreads();
;         int it = *sh;
;         if (mode == 1) { if (it >= 192) break; }
;         else if (mode == 2) { if (it >= 512) break; it += 208; }
;         const int ntot = 192 + 16 + 512 + 1024 + N_CONV_FFN + (l == 0 ? N_CONV_MIX : 0);
;         if (it >= ntot) break;
;         unsigned* flags = (unsigned*)(WS(p) + OFF_CTRL) + 16 + l * 16;
;         if (it < 192) { if (EN(20)) rwkv_scan2_item(p, it, lds); }
;         else if (it < 208) { if (EN(21)) ml_p2_item(p, it - 192, flags + (it - 192), lds); }
;         else if (it < 720) { const int a = it - 208; if (EN(22)) attn_item(p, l, a & 15, 31 - (a >> 4), lds); }
.LBB0_152:
	s_andn2_b64 vcc, exec, s[24:25]
	s_cbranch_vccnz .LBB0_705
	v_readlane_b32 s2, v255, 13
	s_cmp_lt_i32 s2, 1
	s_mov_b64 s[24:25], -1
	s_cbranch_scc1 .LBB0_642
	v_readlane_b32 s2, v255, 13
	s_cmp_gt_i32 s2, 1
	s_cbranch_scc0 .LBB0_522
	s_mov_b32 s2, s89
	s_add_u32 s24, s46, s2
	s_addc_u32 s25, s47, 0
	s_ashr_i32 s65, s64, 31
	s_lshl_b64 s[2:3], s[64:65], 2
	s_add_u32 s34, s24, s2
	s_addc_u32 s35, s25, s3
	v_readlane_b32 s2, v255, 11
	v_readlane_b32 s3, v255, 12
	s_and_b64 s[2:3], s[2:3], exec
	s_movk_i32 s2, 0x12c0
	s_mov_b32 s6, s64
	s_cselect_b32 s64, s2, 0xf10
	s_lshl_b32 s4, s6, 2
	v_writelane_b32 v255, s4, 18
	s_mov_b32 s4, s6
	v_writelane_b32 v255, s4, 16
	s_lshl_b32 s2, s6, 4
	s_mul_hi_i32 s30, s6, 0xb00000
	s_mul_i32 s31, s6, 0xb00000
	s_lshl_b32 s24, s6, 10
	s_lshl_b32 s26, s6, 8
	v_writelane_b32 v255, s5, 17
	s_lshl_b32 s28, s6, 9
	v_readlane_b32 s4, v252, 35
	s_ashr_i32 s3, s2, 31
	s_ashr_i32 s25, s24, 31
	s_ashr_i32 s27, s26, 31
	s_ashr_i32 s29, s28, 31
	v_readlane_b32 s6, v252, 37
	v_readlane_b32 s14, v252, 45
	v_readlane_b32 s7, v252, 38
	v_readlane_b32 s15, v252, 46
	s_add_u32 s6, s14, s31
	v_readlane_b32 s10, v252, 41
	s_addc_u32 s7, s15, s30
	v_readlane_b32 s11, v252, 42
	s_add_u32 s10, s10, s31
	v_readlane_b32 s12, v252, 43
	v_writelane_b32 v255, s6, 14
	s_addc_u32 s11, s11, s30
	v_readlane_b32 s13, v252, 44
	v_writelane_b32 v255, s7, 15
	s_add_u32 s6, s12, s31
	v_readlane_b32 s8, v252, 39
	v_writelane_b32 v255, s6, 24
	s_addc_u32 s6, s13, s30
	s_lshl_b64 s[24:25], s[24:25], 2
	v_readlane_b32 s9, v252, 40
	v_writelane_b32 v255, s6, 25
	s_add_u32 s8, s8, s24
	v_readlane_b32 s6, v254, 27
	s_addc_u32 s9, s9, s25
	v_readlane_b32 s7, v254, 28
	v_writelane_b32 v255, s11, 26
	s_and_b64 s[30:31], s[6:7], exec
	v_writelane_b32 v255, s10, 27
	v_readlane_b32 s16, v252, 47
	v_readlane_b32 s17, v252, 48
	v_readlane_b32 s18, v252, 49
	v_readlane_b32 s19, v252, 50
	s_cselect_b32 s7, s11, s9
	v_writelane_b32 v255, s8, 28
	s_cselect_b32 s6, s10, s8
	v_readlane_b32 s5, v252, 36
	v_writelane_b32 v255, s9, 29
	v_readlane_b32 s8, v252, 19
	v_readlane_b32 s16, v252, 27
	v_readlane_b32 s17, v252, 28
	s_add_u32 s44, s16, s24
	v_readlane_b32 s18, v252, 29
	v_readlane_b32 s22, v252, 33
	s_addc_u32 s45, s17, s25
	s_lshl_b64 s[24:25], s[26:27], 2
	v_readlane_b32 s19, v252, 30
	v_readlane_b32 s23, v252, 34
	s_add_u32 s22, s18, s24
	v_writelane_b32 v255, s6, 30
	s_addc_u32 s23, s19, s25
	s_add_u32 s4, s4, s24
	v_writelane_b32 v255, s7, 31
	v_readlane_b32 s9, v252, 20
	v_readlane_b32 s10, v252, 21
	v_readlane_b32 s11, v252, 22
	v_readlane_b32 s12, v252, 23
	v_readlane_b32 s13, v252, 24
	v_readlane_b32 s14, v252, 25
	v_readlane_b32 s15, v252, 26
	v_writelane_b32 v255, s4, 20
	s_addc_u32 s4, s5, s25
	v_writelane_b32 v255, s4, 22
	v_readlane_b32 s4, v252, 3
	s_lshl_b64 s[24:25], s[28:29], 2
	v_readlane_b32 s9, v252, 8
	v_readlane_b32 s5, v252, 4
	v_readlane_b32 s10, v252, 9
	s_add_u32 s9, s4, s24
	v_readlane_b32 s11, v252, 10
	s_addc_u32 s10, s5, s25
	s_lshl_b64 s[2:3], s[2:3], 2
	v_readlane_b32 s20, v252, 31
	v_readlane_b32 s21, v252, 32
	s_add_u32 s11, s46, s2
	s_mov_b64 s[20:21], s[34:35]
	s_addc_u32 s65, s47, s3
	v_readlane_b32 s6, v252, 5
	v_readlane_b32 s7, v252, 6
	v_readlane_b32 s8, v252, 7
	v_readlane_b32 s12, v252, 11
	v_readlane_b32 s13, v252, 12
	v_readlane_b32 s14, v252, 13
	v_readlane_b32 s15, v252, 14
	v_readlane_b32 s16, v252, 15
	v_readlane_b32 s17, v252, 16
	v_readlane_b32 s18, v252, 17
	v_readlane_b32 s19, v252, 18
	s_waitcnt lgkmcnt(0)
	s_mov_b32 s2, 0
	s_cmpk_lg_u32 s77, 0x200
	s_cbranch_scc1 .Lplace_off
	s_movk_i32 s2, 0xc0
.Lplace_off:
	s_nop 0
	v_writelane_b32 v255, s2, 45
	s_cmp_eq_u32 s2, 0
	s_cbranch_scc1 .LBB0_159
	v_readlane_b32 s78, v252, 0
	s_nop 0
	s_and_b32 s2, s78, 0xff
	s_cmpk_ge_u32 s2, 96
	s_cbranch_scc1 .Lplace_q
	s_lshl_b32 s2, s2, 1
	s_lshr_b32 s78, s78, 8
	s_add_u32 s78, s78, s2
	s_branch .Lsc_entry

; __device__ __forceinline__ int opaque_tid() { int t = threadIdx.x; asm volatile("" : "+v"(t)); return t; }
; __device__ __forceinline__ void run_phase(const Params& p, int ph, char* lds, int mode) {
;     ...
;         __syncthreads();
;         if (opaque_tid() == 0) *sh = (int)atomicAdd(ctr, 1u);
;         __syncthreads();
;         int it = *sh;
;         if (mode == 1) { if (it >= 192) break; }
;         else if (mode == 2) { if (it >= 512) break; it += 208; }
;         const int ntot = 192 + 16 + 512 + 1024 + N_CONV_FFN + (l == 0 ? N_CONV_MIX : 0);
;         if (it >= ntot) break;
.LBB0_163:
	s_movk_i32 s8, 0x8c8
	s_or_b64 exec, exec, s[24:25]
	v_readlane_b32 s2, v255, 2
	s_waitcnt lgkmcnt(0)
	s_barrier
	v_mov_b32_e32 v0, s2
	v_readlane_b32 vcc_lo, v255, 45
	ds_read_b32 v0, v0
	s_mov_b64 s[24:25], -1
	s_waitcnt lgkmcnt(0)
	v_add_u32_e32 v0, vcc_lo, v0
	v_cmp_le_i32_e32 vcc, s64, v0
	v_readfirstlane_b32 s78, v0
	s_cbranch_vccnz .LBB0_158
	s_mov_b32 s2, s89
	s_cmpk_gt_i32 s78, 0xbf
	s_cbranch_scc0 .LBB0_478
	s_add_u32 s24, s11, s2
	s_addc_u32 s25, s65, 0
	s_cmpk_gt_u32 s78, 0xcf
	s_mov_b64 s[26:27], -1
	s_cbranch_scc0 .LBB0_452
	s_cmpk_gt_u32 s78, 0x2cf
	s_cbranch_scc0 .LBB0_382
	s_cmpk_gt_u32 s78, 0x6cf
	s_cbranch_scc0 .LBB0_328
	s_cmpk_gt_u32 s78, 0xf0f
	s_cbranch_scc0 .LBB0_285
	s_add_i32 s30, s78, 0xfffff0f0
	s_mov_b32 s2, s89
	s_add_u32 s28, s46, s2
	s_addc_u32 s29, s47, 0
	s_cmpk_gt_u32 s30, 0x23f
	s_cbranch_scc0 .LBB0_248
	s_cmpk_gt_u32 s30, 0x26f
	s_cbranch_scc0 .LBB0_211
	s_cmpk_gt_u32 s30, 0x2af
	s_cbranch_scc0 .LBB0_175
; __device__ __forceinline__ void conv_tile(const float* __restrict__ s0, const float* __restrict__ s1, int mode, int K, int Nsrc,
;                           const float* __restrict__ gain, bf16_t* __restrict__ dst, int kt, int nt, char* ldsraw) {
;     ...
;   for (int i = 0; i < 16; i++) {
;     const int idx = tid + 256 * i; const int kk = idx >> 6, nn = idx & 63; const int n = nt * 64 + nn, k = kt * 64 + kk;
;     const float* sp; int col;
;     if (mode == 0) { sp = s0; col = (n < Nsrc) ? n : (Nsrc - 1); }
;     else { const int g = n >> 5, r = n & 31; col = g * 16 + (r & 15); sp = (r < 16) ? s0 : s1; }
;     vals[i] = __builtin_nontemporal_load(sp + (size_t)k * Nsrc + col);
;     gv[i] = gp[k];
;   }
; #pragma unroll
;   for (int i = 0; i < 16; i++) {
;     const int idx = tid + 256 * i; const int kk = idx >> 6, nn = idx & 63; const int n = nt * 64 + nn;
;     float v = gain ? vals[i] * gv[i] : vals[i];
;     if (mode == 0 && n >= Nsrc) v = 0.f;
;     lds[kk * 65 + nn] = v;
;   }
;   __syncthreads();
	s_lshl_b32 s3, s30, 2
	v_mov_b32_e32 v4, v198
	s_and_b32 s3, s3, 0x7fffffc0
	s_add_i32 s88, s3, 0xfffff540
	v_ashrrev_i32_e32 v5, 6, v4
	s_lshl_b32 s2, s30, 6
	v_add_u32_e32 v0, s88, v5
	v_and_b32_e32 v8, 63, v4
	s_and_b32 s2, s2, 0x3c0
	v_ashrrev_i32_e32 v1, 31, v0
	v_readlane_b32 s4, v254, 9
	v_or_b32_e32 v2, s2, v8
	v_lshlrev_b64 v[0:1], 12, v[0:1]
	v_readlane_b32 s5, v254, 10
	v_lshlrev_b32_e32 v2, 2, v2
	s_mov_b32 s3, 0
	v_lshl_add_u64 v[0:1], s[4:5], 0, v[0:1]
	v_lshl_add_u64 v[0:1], v[0:1], 0, v[2:3]
	global_load_dword v9, v[0:1], off nt
	v_add_u32_e32 v0, 0x100, v4
	v_ashrrev_i32_e32 v10, 6, v0
	v_add_u32_e32 v0, s88, v10
	v_ashrrev_i32_e32 v1, 31, v0
	v_lshlrev_b64 v[0:1], 12, v[0:1]
	v_lshl_add_u64 v[0:1], s[4:5], 0, v[0:1]
	v_lshl_add_u64 v[0:1], v[0:1], 0, v[2:3]
	global_load_dword v11, v[0:1], off nt
	v_add_u32_e32 v0, 0x200, v4
	v_ashrrev_i32_e32 v12, 6, v0
	v_add_u32_e32 v0, s88, v12
	v_ashrrev_i32_e32 v1, 31, v0
	v_lshlrev_b64 v[0:1], 12, v[0:1]
	v_lshl_add_u64 v[0:1], s[4:5], 0, v[0:1]
	v_lshl_add_u64 v[0:1], v[0:1], 0, v[2:3]
	global_load_dword v13, v[0:1], off nt
	v_add_u32_e32 v0, 0x300, v4
	v_ashrrev_i32_e32 v14, 6, v0
	v_add_u32_e32 v0, s88, v14
	v_ashrrev_i32_e32 v1, 31, v0
	v_lshlrev_b64 v[0:1], 12, v[0:1]
	v_lshl_add_u64 v[0:1], s[4:5], 0, v[0:1]
	v_lshl_add_u64 v[0:1], v[0:1], 0, v[2:3]
	global_load_dword v15, v[0:1], off nt
	v_add_u32_e32 v0, 0x400, v4
	v_ashrrev_i32_e32 v16, 6, v0
	v_add_u32_e32 v0, s88, v16
	v_ashrrev_i32_e32 v1, 31, v0
	v_lshlrev_b64 v[0:1], 12, v[0:1]
	v_lshl_add_u64 v[0:1], s[4:5], 0, v[0:1]
	v_lshl_add_u64 v[0:1], v[0:1], 0, v[2:3]
	global_load_dword v17, v[0:1], off nt
	v_add_u32_e32 v0, 0x500, v4
	v_ashrrev_i32_e32 v18, 6, v0
	v_add_u32_e32 v0, s88, v18
	v_ashrrev_i32_e32 v1, 31, v0
	v_lshlrev_b64 v[0:1], 12, v[0:1]
	v_lshl_add_u64 v[0:1], s[4:5], 0, v[0:1]
	v_lshl_add_u64 v[0:1], v[0:1], 0, v[2:3]
	global_load_dword v19, v[0:1], off nt
	v_add_u32_e32 v0, 0x600, v4
	v_ashrrev_i32_e32 v20, 6, v0
	v_add_u32_e32 v0, s88, v20
	v_ashrrev_i32_e32 v1, 31, v0
	v_lshlrev_b64 v[0:1], 12, v[0:1]
	v_lshl_add_u64 v[0:1], s[4:5], 0, v[0:1]
	v_lshl_add_u64 v[0:1], v[0:1], 0, v[2:3]
	global_load_dword v21, v[0:1], off nt
	v_add_u32_e32 v0, 0x700, v4
	v_ashrrev_i32_e32 v22, 6, v0
	v_add_u32_e32 v0, s88, v22
	v_ashrrev_i32_e32 v1, 31, v0
	v_lshlrev_b64 v[0:1], 12, v[0:1]
	v_lshl_add_u64 v[0:1], s[4:5], 0, v[0:1]
	v_lshl_add_u64 v[0:1], v[0:1], 0, v[2:3]
	global_load_dword v23, v[0:1], off nt
	v_add_u32_e32 v0, 0x800, v4
	v_ashrrev_i32_e32 v24, 6, v0
	v_add_u32_e32 v0, s88, v24
	v_ashrrev_i32_e32 v1, 31, v0
	v_lshlrev_b64 v[0:1], 12, v[0:1]
	v_lshl_add_u64 v[0:1], s[4:5], 0, v[0:1]
	v_lshl_add_u64 v[0:1], v[0:1], 0, v[2:3]
	global_load_dword v25, v[0:1], off nt
	v_add_u32_e32 v0, 0x900, v4
	v_ashrrev_i32_e32 v26, 6, v0
	v_add_u32_e32 v0, s88, v26
	v_ashrrev_i32_e32 v1, 31, v0
	v_lshlrev_b64 v[0:1], 12, v[0:1]
	v_lshl_add_u64 v[0:1], s[4:5], 0, v[0:1]
	v_lshl_add_u64 v[0:1], v[0:1], 0, v[2:3]
	global_load_dword v27, v[0:1], off nt
	v_add_u32_e32 v0, 0xa00, v4
	v_ashrrev_i32_e32 v28, 6, v0
	v_add_u32_e32 v0, s88, v28
	v_ashrrev_i32_e32 v1, 31, v0
	v_lshlrev_b64 v[0:1], 12, v[0:1]
	v_lshl_add_u64 v[0:1], s[4:5], 0, v[0:1]
	v_lshl_add_u64 v[0:1], v[0:1], 0, v[2:3]
	global_load_dword v29, v[0:1], off nt
	v_add_u32_e32 v0, 0xb00, v4
	v_ashrrev_i32_e32 v30, 6, v0
	v_add_u32_e32 v0, s88, v30
	v_ashrrev_i32_e32 v1, 31, v0
	v_lshlrev_b64 v[0:1], 12, v[0:1]
	v_lshl_add_u64 v[0:1], s[4:5], 0, v[0:1]
	v_lshl_add_u64 v[0:1], v[0:1], 0, v[2:3]
	global_load_dword v31, v[0:1], off nt
	v_add_u32_e32 v0, 0xc00, v4
	v_ashrrev_i32_e32 v32, 6, v0
	v_add_u32_e32 v0, s88, v32
	v_ashrrev_i32_e32 v1, 31, v0
	v_lshlrev_b64 v[0:1], 12, v[0:1]
	v_lshl_add_u64 v[0:1], s[4:5], 0, v[0:1]
	v_lshl_add_u64 v[0:1], v[0:1], 0, v[2:3]
	global_load_dword v33, v[0:1], off nt
	v_add_u32_e32 v0, 0xd00, v4
	v_ashrrev_i32_e32 v34, 6, v0
	v_add_u32_e32 v0, s88, v34
	v_ashrrev_i32_e32 v1, 31, v0
	v_lshlrev_b64 v[0:1], 12, v[0:1]
	v_lshl_add_u64 v[0:1], s[4:5], 0, v[0:1]
	v_lshl_add_u64 v[0:1], v[0:1], 0, v[2:3]
	global_load_dword v35, v[0:1], off nt
	v_add_u32_e32 v0, 0xe00, v4
	v_ashrrev_i32_e32 v36, 6, v0
	v_add_u32_e32 v0, s88, v36
	v_ashrrev_i32_e32 v1, 31, v0
	v_lshlrev_b64 v[0:1], 12, v[0:1]
	v_lshl_add_u64 v[0:1], s[4:5], 0, v[0:1]
	v_lshl_add_u64 v[0:1], v[0:1], 0, v[2:3]
	global_load_dword v37, v[0:1], off nt
	v_add_u32_e32 v0, 0xf00, v4
	v_ashrrev_i32_e32 v38, 6, v0
	v_add_u32_e32 v0, s88, v38
	v_ashrrev_i32_e32 v1, 31, v0
	v_lshlrev_b64 v[0:1], 12, v[0:1]
	v_lshl_add_u64 v[0:1], s[4:5], 0, v[0:1]
	v_lshl_add_u64 v[0:1], v[0:1], 0, v[2:3]
	global_load_dword v2, v[0:1], off nt
	v_lshl_add_u32 v0, v8, 2, 0
	v_mad_u64_u32 v[6:7], s[26:27], v5, s71, v[0:1]
	s_waitcnt vmcnt(15)
	ds_write_b32 v6, v9
	v_mad_u64_u32 v[6:7], s[26:27], v10, s71, v[0:1]
	s_waitcnt vmcnt(14)
	ds_write_b32 v6, v11
	v_mad_u64_u32 v[6:7], s[26:27], v12, s71, v[0:1]
	s_waitcnt vmcnt(13)
	ds_write_b32 v6, v13
	v_mad_u64_u32 v[6:7], s[26:27], v14, s71, v[0:1]
	s_waitcnt vmcnt(12)
	ds_write_b32 v6, v15
	v_mad_u64_u32 v[6:7], s[26:27], v16, s71, v[0:1]
	s_waitcnt vmcnt(11)
	ds_write_b32 v6, v17
	v_mad_u64_u32 v[6:7], s[26:27], v18, s71, v[0:1]
	s_waitcnt vmcnt(10)
	ds_write_b32 v6, v19
	v_mad_u64_u32 v[6:7], s[26:27], v20, s71, v[0:1]
	s_waitcnt vmcnt(9)
	ds_write_b32 v6, v21
	v_mad_u64_u32 v[6:7], s[26:27], v22, s71, v[0:1]
	s_waitcnt vmcnt(8)
	ds_write_b32 v6, v23
	v_mad_u64_u32 v[6:7], s[26:27], v24, s71, v[0:1]
	s_waitcnt vmcnt(7)
	ds_write_b32 v6, v25
	v_mad_u64_u32 v[6:7], s[26:27], v26, s71, v[0:1]
	v_mad_u32_u24 v5, v8, s71, 0
	s_waitcnt vmcnt(6)
	ds_write_b32 v6, v27
	v_mad_u64_u32 v[6:7], s[26:27], v28, s71, v[0:1]
	s_waitcnt vmcnt(5)
	ds_write_b32 v6, v29
	v_mad_u64_u32 v[6:7], s[26:27], v30, s71, v[0:1]
	s_waitcnt vmcnt(4)
	ds_write_b32 v6, v31
	v_mad_u64_u32 v[6:7], s[26:27], v32, s71, v[0:1]
	s_waitcnt vmcnt(3)
	ds_write_b32 v6, v33
	v_mad_u64_u32 v[6:7], s[26:27], v34, s71, v[0:1]
	s_waitcnt vmcnt(2)
	ds_write_b32 v6, v35
	v_mad_u64_u32 v[6:7], s[26:27], v36, s71, v[0:1]
	v_mad_u64_u32 v[0:1], s[26:27], v38, s71, v[0:1]
	s_lshl_b64 s[26:27], s[88:89], 1
	s_add_u32 s26, s28, s26
	s_addc_u32 s27, s29, s27
	s_waitcnt vmcnt(1)
	ds_write_b32 v6, v37
	s_waitcnt vmcnt(0)
	ds_write_b32 v0, v2
	v_lshlrev_b32_e32 v2, 1, v8
	v_lshl_add_u64 v[0:1], s[26:27], 0, v[2:3]
	s_mov_b64 s[26:27], 0xf94c000
	v_lshl_add_u64 v[0:1], v[0:1], 0, s[26:27]
	s_waitcnt lgkmcnt(0)
	s_barrier

; __device__ __forceinline__ void rwkv_scan2_item(const Params& p, int item, char* ldsraw) {
;     ...
;   const int bh = item / 12, rr = item - bh * 12, b = bh >> 2, h = bh & 3;
;   const int seg = (rr >= 4) ? 1 : 0, ident = (rr >= 8) ? 1 : 0, r16 = rr & 3;
;   const int c0 = seg * 128;
;   const int tid = opaque_tid(), lane = tid & 63, wid = tid >> 6, jl = lane & 15, rl = lane >> 4;
;   const int isY = wid >> 1, row8 = (wid & 1) * 4 + rl;
;   const int rowA = r16 * 16 + row8;
;   const int st = tid >> 4, part = tid & 15;
;   f32x4 pw; u32x2 pkk, pkka, pk, pwr; unsigned short pv; float pc;
;   auto load = [&](int chunk) {
;     const size_t base = (size_t)bh * S + chunk * 16 + st;
;     pw = *(const f32x4*)(RW + base * 64 + part * 4);
;     const bf16_t* rb = RB + base * 320;
;     pkk = *(const u32x2*)(rb + part * 4); pkka = *(const u32x2*)(rb + 64 + part * 4);
;     pk = *(const u32x2*)(rb + 128 + part * 4); pwr = *(const u32x2*)(rb + 192 + part * 4);
;     pv = rb[256 + r16 * 16 + part];
;     pc = (part < 2) ? RC[base * 4 + part] : 0.f;
;   };
;   auto store = [&](int bi) {
;     float* d = buf + bi * CH + st * STEP;
;     *(f32x4*)(d + part * 4) = pw;
;     *(f32x4*)(d + 64 + part * 4) = (f32x4){bflo(pkk[0]), bfhi(pkk[0]), bflo(pkk[1]), bfhi(pkk[1])};
;     *(f32x4*)(d + 128 + part * 4) = (f32x4){bflo(pkka[0]), bfhi(pkka[0]), bflo(pkka[1]), bfhi(pkka[1])};
;     *(f32x4*)(d + 192 + part * 4) = (f32x4){bflo(pk[0]), bfhi(pk[0]), bflo(pk[1]), bfhi(pk[1])};
;     *(f32x4*)(d + 256 + part * 4) = (f32x4){bflo(pwr[0]), bfhi(pwr[0]), bflo(pwr[1]), bfhi(pwr[1])};
;     d[320 + part] = ident ? 0.f : bf2f(pv);
;     if (part < 2) d[336 + part] = pc;
;   };
;   load(c0); store(0); __syncthreads();
;   float a0 = 0.f, a1 = 0.f, a2 = 0.f, a3 = 0.f, b0 = 0.f, b1 = 0.f, b2 = 0.f, b3 = 0.f;
;   if (ident) {
;     const int mA = rowA - jl * 4, mB = mA + 8;
;     a0 = (mA == 0) ? 1.f : 0.f; a1 = (mA == 1) ? 1.f : 0.f; a2 = (mA == 2) ? 1.f : 0.f; a3 = (mA == 3) ? 1.f : 0.f;
;     b0 = (mB == 0) ? 1.f : 0.f; b1 = (mB == 1) ? 1.f : 0.f; b2 = (mB == 2) ? 1.f : 0.f; b3 = (mB == 3) ? 1.f : 0.f;
;   }
;   bf16_t* yout = ident ? (bf16_t*)(WS(p) + OFF_Z) + ((size_t)bh * 2048 + jl) * 64 + rowA
;                        : Yb + ((size_t)b * S + c0 * 16 + jl) * 1024 + 512 + h * 64 + rowA;
;   const size_t ystride = ident ? (size_t)16 * 64 : (size_t)16 * 1024;
;   int bi = 0;
.Lsc_entry:
	s_mul_i32 s2, s78, 0xaaab
	s_lshr_b32 s2, s2, 19
	s_mul_i32 s3, s2, 12
	s_sub_u32 s3, s78, s3
	s_and_b32 s4, s3, 3
	s_lshr_b32 s41, s3, 2
	s_cmp_lg_u32 s41, 0
	s_cselect_b32 s42, 0x800, 0
	s_lshl_b32 s88, s2, 12
	s_add_u32 s88, s88, s42
	s_lshl_b32 s24, s88, 8
	s_add_u32 s24, s24, 0x87a8000
	s_add_u32 s24, s46, s24
	s_addc_u32 s25, s47, 0
	s_mul_i32 s26, s88, 640
	s_add_u32 s26, s26, 0x97a8000
	s_add_u32 s26, s46, s26
	s_addc_u32 s27, s47, 0
	s_lshl_b32 s28, s88, 4
	s_add_u32 s28, s28, 0xbfa8000
	s_add_u32 s28, s46, s28
	s_addc_u32 s29, s47, 0
	s_lshr_b32 s30, s2, 2
	s_lshl_b32 s30, s30, 12
	s_add_u32 s30, s30, s42
	s_lshl_b32 s30, s30, 11
	s_and_b32 s88, s2, 3
	s_lshl_b32 s88, s88, 7
	s_add_u32 s30, s30, s88
	s_add_u32 s30, s30, 0xc0a8400
	s_lshl_b32 s88, s2, 18
	s_add_u32 s88, s88, 0xfb4c000
	s_cmp_eq_u32 s41, 2
	s_cselect_b32 s30, s88, s30
	s_mov_b32 s40, 0x8000
	s_cselect_b32 s40, 0x800, s40
	s_cselect_b32 s88, 7, 11
	s_add_u32 s30, s46, s30
	s_addc_u32 s31, s47, 0
	s_mov_b32 s34, 0xaaaaaaaa
	s_mov_b32 s35, 0xaaaaaaaa
	s_mov_b32 s36, 0xcccccccc
	s_mov_b32 s37, 0xcccccccc
	v_and_b32_e32 v17, 15, v198
	v_lshrrev_b32_e32 v18, 4, v198
	v_and_b32_e32 v18, 15, v18
	v_bfrev_b32_e32 v19, v17
	v_lshrrev_b32_e32 v19, 28, v19
	v_lshlrev_b32_e32 v0, 4, v17
	v_lshlrev_b32_e32 v1, 6, v18
	v_add_u32_e32 v1, 0x5000, v1
	s_movk_i32 s42, 0x500
	v_mad_u32_u24 v2, v18, s42, v0
	v_lshlrev_b32_e32 v8, 6, v17
	v_lshl_add_u32 v8, v18, 2, v8
	v_add_u32_e32 v8, 0x5000, v8
	v_lshlrev_b32_e32 v9, 3, v18
	v_add_u32_e32 v9, 0x5400, v9
	v_lshl_add_u32 v10, v19, 2, v1
	v_lshlrev_b32_e32 v11, 3, v19
	v_add_u32_e32 v11, 0x5400, v11
	v_lshlrev_b32_e32 v12, 8, v18
	v_add_u32_e32 v12, v12, v0
	s_movk_i32 s42, 0x280
	v_mul_u32_u24_e32 v14, s42, v18
	v_lshl_add_u32 v13, v17, 3, v14
	v_lshl_add_u32 v14, v17, 1, v14
	s_lshl_b32 s42, s4, 5
	s_add_u32 s42, s42, 0x200
	v_add_u32_e32 v14, s42, v14
	v_lshlrev_b32_e32 v15, 4, v18
	s_lshl_b32 s42, s4, 4
	v_add_u32_e32 v18, s42, v18
	v_lshlrev_b32_e32 v16, s88, v19
	v_lshl_add_u32 v16, v18, 1, v16
	v_mov_b32_e32 v4, 0
	v_mov_b32_e32 v5, 0
	v_mov_b32_e32 v6, 0
	v_mov_b32_e32 v7, 0
	v_mov_b32_e32 v108, 0
	v_mov_b32_e32 v109, 0
	v_mov_b32_e32 v110, 0
	v_mov_b32_e32 v111, 0
	s_cmp_lg_u32 s41, 2
	s_cbranch_scc1 .Lsc_noident
	v_lshlrev_b32_e32 v17, 2, v17
	v_sub_u32_e32 v17, v18, v17
	v_cmp_eq_u32_e32 vcc, 0, v17
	s_nop 1
	v_cndmask_b32_e64 v4, 0, 1.0, vcc
	v_cmp_eq_u32_e32 vcc, 1, v17
	s_nop 1
	v_cndmask_b32_e64 v5, 0, 1.0, vcc
	v_cmp_eq_u32_e32 vcc, 2, v17
	s_nop 1
	v_cndmask_b32_e64 v6, 0, 1.0, vcc
	v_cmp_eq_u32_e32 vcc, 3, v17
	s_nop 1
	v_cndmask_b32_e64 v7, 0, 1.0, vcc
